# attention: K/V LDS staging writes spread one per MFMA gap across 8 PV MFMAs
# speedup vs baseline: 1.1404x; 1.0039x over previous
; template <bool SAMPLE>
; DEV void attn_unit(CParams& p, int layer, int unit, float lam, float lam_init, char* lds, const int swave) {
;     ...
;   for (int t = 0; t < ntiles; ++t) {
;     const int tn = SAMPLE ? t + 1 : (t + 1 < ntiles ? t + 1 : t);
;     if (!SAMPLE || t + 1 < ntiles) gloadK(tn);
;     if (t < my_tiles) {
;       const char* Ks = lds + (t & 1) * A_BUF; const char* Vs = Ks + A_KT;
;       bf16x8 pf[2][4];
;       f32x16 S0, S1;
;       auto qk = [&](int br) {
;         const f32x16 zc = {0.f, 0.f, 0.f, 0.f, 0.f, 0.f, 0.f, 0.f, 0.f, 0.f, 0.f, 0.f, 0.f, 0.f, 0.f, 0.f};
; #pragma unroll
;         for (int ks = 0; ks < 4; ++ks) {
;           const bf16x8 k0 = lds_read8(Ks + lr * AK_B + (br * 64 + ks * 16 + hh * 8) * 2);
;           const bf16x8 k1 = lds_read8(Ks + (32 + lr) * AK_B + (br * 64 + ks * 16 + hh * 8) * 2);
;           S0 = mfma32(k0, qf[br][ks], ks == 0 ? zc : S0); S1 = mfma32(k1, qf[br][ks], ks == 0 ? zc : S1);
;         }
;         if (sample && t == 32) {
; #pragma unroll
;           for (int r = 0; r < 16; ++r) { if (r >= 8) S0[r] = -1e30f; S1[r] = -1e30f; }
;         }
;       };
;       auto sm8 = [&](const f32x16& Sx, int r0, float nm, float& lsum) -> bf16x8 {
;         f32x2 c2; c2[0] = cexp; c2[1] = cexp;
;         f32x2 nm2; nm2[0] = nm; nm2[1] = nm;
;         union { u32x4 u; bf16x8 b; } x;
;         f32x2 sum2; sum2[0] = 0.f; sum2[1] = 0.f;
; #pragma unroll
;         for (int r = 0; r < 8; r += 2) {
;           f32x2 v; v[0] = Sx[r0 + r]; v[1] = Sx[r0 + r + 1];
;           v = v * c2 + nm2;
;           f32x2 ex; ex[0] = __builtin_amdgcn_exp2f(v[0]); ex[1] = __builtin_amdgcn_exp2f(v[1]);
;           sum2 += ex;
;           x.u[r >> 1] = pk2(ex[0], ex[1]);
;         }
;         lsum += sum2[0] + sum2[1];
;         return x.b;
;       };
;       qk(0);
;       pf[0][0] = sm8(S0, 0, nmc[0], ls[0]); pf[0][1] = sm8(S0, 8, nmc[0], ls[0]);
;       pf[0][2] = sm8(S1, 0, nmc[0], ls[0]); pf[0][3] = sm8(S1, 8, nmc[0], ls[0]);
;       qk(1);
;       if (!SAMPLE || t + 1 < ntiles) gloadV(tn);
; #pragma unroll
;       for (int sl = 0; sl < 4; ++sl) {
; #pragma unroll
;         for (int e = 0; e < 4; ++e) {
;           const bf16x8 vf = tr8(Vs, AV_B, sl * 16, e * 32, lane);
;           O1[e] = mfma32(vf, pf[0][sl], O1[e]);
;         }
;         pf[1][sl] = sm8(sl < 2 ? S0 : S1, (sl & 1) * 8, nmc[1], ls[1]);
.LBB0_243:
	s_add_i32 s36, s37, 1
	s_cmp_ge_u32 s36, s23
	s_cselect_b64 s[6:7], -1, 0
	s_cmp_lt_u32 s36, s23
	s_cselect_b32 s100, s36, s37
	s_lshl_b32 s101, s100, 6
	s_cmp_ge_u32 s37, s29
	s_cbranch_scc1 .LBB0_245
	s_bitcmp1_b32 s37, 0
	s_cselect_b32 s38, 0x9400, 0
	s_add_i32 s38, s38, 16
	v_add_u32_e32 v118, s38, v243
	ds_read_b128 v[62:65], v118
	ds_read_b128 v[66:69], v118 offset:32
	s_waitcnt lgkmcnt(1)
	v_mfma_f32_32x32x16_bf16 v[178:193], v[62:65], v[16:19], 0
	s_add_i32 s8, s101, s28
	s_mul_hi_i32 s9, s8, 0xc00
	s_mulk_i32 s8, 0xc00
	s_or_b64 s[8:9], s[8:9], s[2:3]
	v_lshl_add_u64 v[54:55], s[8:9], 1, v[50:51]
	global_load_dwordx4 a[160:163], v[54:55], off
	global_load_dwordx4 a[144:147], v[54:55], off offset:1024
	ds_read_b128 v[62:65], v118 offset:8704
	ds_read_b128 v[70:73], v118 offset:8736
	s_waitcnt lgkmcnt(1)
	v_mfma_f32_32x32x16_bf16 v[210:225], v[62:65], v[16:19], 0
	s_add_i32 s8, s30, s101
	s_mul_hi_i32 s9, s8, 0xc00
	s_mulk_i32 s8, 0xc00
	s_or_b64 s[8:9], s[8:9], s[2:3]
	v_lshl_add_u64 v[56:57], s[8:9], 1, v[50:51]
	global_load_dwordx4 a[164:167], v[56:57], off
	global_load_dwordx4 a[148:151], v[56:57], off offset:1024
	v_mfma_f32_32x32x16_bf16 v[178:193], v[66:69], v[20:23], v[178:193]
	s_add_i32 s8, s31, s101
	s_mul_hi_i32 s9, s8, 0xc00
	s_mulk_i32 s8, 0xc00
	s_or_b64 s[8:9], s[8:9], s[2:3]
	v_lshl_add_u64 v[58:59], s[8:9], 1, v[50:51]
	global_load_dwordx4 a[168:171], v[58:59], off
	global_load_dwordx4 a[152:155], v[58:59], off offset:1024
	ds_read_b128 v[62:65], v118 offset:64
	ds_read_b128 v[66:69], v118 offset:96
	s_waitcnt lgkmcnt(2)
	v_mfma_f32_32x32x16_bf16 v[210:225], v[70:73], v[20:23], v[210:225]
	s_add_i32 s8, s34, s101
	s_mul_hi_i32 s9, s8, 0xc00
	s_mulk_i32 s8, 0xc00
	s_or_b64 s[8:9], s[8:9], s[2:3]
	v_lshl_add_u64 v[60:61], s[8:9], 1, v[50:51]
	global_load_dwordx4 a[172:175], v[60:61], off
	global_load_dwordx4 a[156:159], v[60:61], off offset:1024
	s_waitcnt lgkmcnt(1)
	v_mfma_f32_32x32x16_bf16 v[178:193], v[62:65], v[24:27], v[178:193]
	ds_read_b128 v[62:65], v118 offset:8768
	ds_read_b128 v[70:73], v118 offset:8800
	ds_read_b128 v[88:91], v118 offset:128
	s_waitcnt lgkmcnt(2)
	v_mfma_f32_32x32x16_bf16 v[210:225], v[62:65], v[24:27], v[210:225]
	s_waitcnt lgkmcnt(0)
	v_mfma_f32_32x32x16_bf16 v[226:241], v[88:91], v[32:35], 0
	v_mfma_f32_32x32x16_bf16 v[178:193], v[66:69], v[28:31], v[178:193]
	s_nop 11
	v_fma_f32 v102, v180, s52, v48
	v_fma_f32 v103, v181, s52, v49
	v_fma_f32 v62, v184, s52, v48
	v_fma_f32 v63, v185, s52, v49
	v_fma_f32 v66, v190, s52, v48
	v_fma_f32 v67, v191, s52, v49
	v_mfma_f32_32x32x16_bf16 v[210:225], v[70:73], v[28:31], v[210:225]
	ds_read_b128 v[68:71], v118 offset:8832
	ds_read_b128 v[92:95], v118 offset:160
	ds_read_b128 v[88:91], v118 offset:8864
	s_waitcnt lgkmcnt(2)
	v_exp_f32_e32 v66, v66
	v_mfma_f32_32x32x16_bf16 v[194:209], v[68:71], v[32:35], 0
	s_waitcnt lgkmcnt(1)
	v_exp_f32_e32 v67, v67
	v_fma_f32 v64, v192, s52, v48
	v_fma_f32 v65, v193, s52, v49
	s_nop 1
	v_fma_f32 v74, v218, s52, v48
	v_mfma_f32_32x32x16_bf16 v[226:241], v[92:95], v[36:39], v[226:241]
	ds_read_b128 v[92:95], v118 offset:192
	s_waitcnt lgkmcnt(1)
	v_fma_f32 v75, v219, s52, v49
	v_fma_f32 v72, v220, s52, v48
	v_fma_f32 v73, v221, s52, v49
	v_exp_f32_e32 v74, v74
	v_mfma_f32_32x32x16_bf16 v[194:209], v[88:91], v[36:39], v[194:209]
	v_fma_f32 v88, v178, s52, v48
	v_fma_f32 v89, v179, s52, v49
	v_exp_f32_e32 v100, v88
	v_exp_f32_e32 v101, v89
	ds_read_b128 v[88:91], v118 offset:8896
	ds_read_b128 v[96:99], v118 offset:224
	s_waitcnt lgkmcnt(2)
	v_mfma_f32_32x32x16_bf16 v[226:241], v[92:95], v[40:43], v[226:241]
	v_exp_f32_e32 v94, v102
	v_exp_f32_e32 v95, v103
	v_cvt_pk_bf16_f32 v92, v100, v101
	v_add_f32_e32 v116, v94, v100
	v_add_f32_e32 v117, v95, v101
	ds_read_b128 v[100:103], v118 offset:8928
	s_waitcnt lgkmcnt(2)
	v_mfma_f32_32x32x16_bf16 v[194:209], v[88:91], v[40:43], v[194:209]
	v_add3_u32 v108, s38, v87, v86
	v_fma_f32 v88, v182, s52, v48
	v_fma_f32 v89, v183, s52, v49
	v_exp_f32_e32 v90, v62
	v_exp_f32_e32 v88, v88
	v_exp_f32_e32 v89, v89
	v_exp_f32_e32 v91, v63
	v_add_f32_e32 v62, v88, v116
	v_add_f32_e32 v63, v89, v117
	ds_read_b64_tr_b16 v[116:117], v108 offset:17408
	ds_read_b64_tr_b16 v[118:119], v108 offset:19968
	s_waitcnt lgkmcnt(2)
	v_mfma_f32_32x32x16_bf16 v[194:209], v[100:103], v[44:47], v[194:209]
	ds_read_b64_tr_b16 v[100:101], v108 offset:17472
	ds_read_b64_tr_b16 v[122:123], v108 offset:17536
	ds_read_b64_tr_b16 v[142:143], v108 offset:17600
	ds_read_b64_tr_b16 v[102:103], v108 offset:20032
	ds_read_b64_tr_b16 v[124:125], v108 offset:20096
	ds_read_b64_tr_b16 v[144:145], v108 offset:20160
	v_mfma_f32_32x32x16_bf16 v[226:241], v[96:99], v[44:47], v[226:241]
	s_waitcnt lgkmcnt(6)
	v_cvt_pk_bf16_f32 v93, v94, v95
	v_cvt_pk_bf16_f32 v94, v88, v89
	v_cvt_pk_bf16_f32 v95, v90, v91
	v_fma_f32 v88, v186, s52, v48
	v_fma_f32 v89, v187, s52, v49
	v_mfma_f32_32x32x16_bf16 a[0:15], v[116:119], v[92:95], a[0:15]
	ds_read_b64_tr_b16 v[146:147], v108 offset:22528
	ds_read_b64_tr_b16 v[148:149], v108 offset:25088
	s_waitcnt lgkmcnt(4)
	v_add_f32_e32 v62, v90, v62
	v_add_f32_e32 v63, v91, v63
	v_exp_f32_e32 v88, v88
	v_mfma_f32_32x32x16_bf16 a[32:47], v[100:103], v[92:95], a[32:47]
	ds_read_b64_tr_b16 v[150:151], v108 offset:22592
	ds_read_b64_tr_b16 v[154:155], v108 offset:22656
	ds_read_b64_tr_b16 v[158:159], v108 offset:22720
	ds_read_b64_tr_b16 v[152:153], v108 offset:25152
	ds_read_b64_tr_b16 v[156:157], v108 offset:25216
	ds_read_b64_tr_b16 v[160:161], v108 offset:25280
	s_waitcnt lgkmcnt(9)
	v_mfma_f32_32x32x16_bf16 a[64:79], v[122:125], v[92:95], a[64:79]
	s_waitcnt lgkmcnt(8)
; DEV uint32_t pk2(float lo, float hi) { f32x2 v; v[0] = lo; v[1] = hi; bf16v2 b = __builtin_convertvector(v, bf16v2); return __builtin_bit_cast(uint32_t, b); }
; DEV f32x16 mfma32(bf16x8 a, bf16x8 b, f32x16 c) { return __builtin_amdgcn_mfma_f32_32x32x16_bf16(a, b, c, 0, 0, 0); }
; template <bool SAMPLE>
; DEV void attn_unit(CParams& p, int layer, int unit, float lam, float lam_init, char* lds, const int swave) {
;     ...
;       auto sm8 = [&](const f32x16& Sx, int r0, float nm, float& lsum) -> bf16x8 {
;         f32x2 c2; c2[0] = cexp; c2[1] = cexp;
;         f32x2 nm2; nm2[0] = nm; nm2[1] = nm;
;         union { u32x4 u; bf16x8 b; } x;
;         f32x2 sum2; sum2[0] = 0.f; sum2[1] = 0.f;
; #pragma unroll
;         for (int r = 0; r < 8; r += 2) {
;           f32x2 v; v[0] = Sx[r0 + r]; v[1] = Sx[r0 + r + 1];
;           v = v * c2 + nm2;
;           f32x2 ex; ex[0] = __builtin_amdgcn_exp2f(v[0]); ex[1] = __builtin_amdgcn_exp2f(v[1]);
;           sum2 += ex;
;           x.u[r >> 1] = pk2(ex[0], ex[1]);
;         }
;         lsum += sum2[0] + sum2[1];
;         return x.b;
;       };
;       qk(0);
;       pf[0][0] = sm8(S0, 0, nmc[0], ls[0]); pf[0][1] = sm8(S0, 8, nmc[0], ls[0]);
;       pf[0][2] = sm8(S1, 0, nmc[0], ls[0]); pf[0][3] = sm8(S1, 8, nmc[0], ls[0]);
;       qk(1);
;       if (!SAMPLE || t + 1 < ntiles) gloadV(tn);
; #pragma unroll
;       for (int sl = 0; sl < 4; ++sl) {
; #pragma unroll
;         for (int e = 0; e < 4; ++e) {
;           const bf16x8 vf = tr8(Vs, AV_B, sl * 16, e * 32, lane);
;           O1[e] = mfma32(vf, pf[0][sl], O1[e]);
;         }
;         pf[1][sl] = sm8(sl < 2 ? S0 : S1, (sl & 1) * 8, nmc[1], ls[1]);
	v_exp_f32_e32 v89, v89
	v_fma_f32 v90, v188, s52, v48
	v_fma_f32 v91, v189, s52, v49
	v_exp_f32_e32 v90, v90
	v_mfma_f32_32x32x16_bf16 a[96:111], v[142:145], v[92:95], a[96:111]
	ds_read_b64_tr_b16 v[162:163], v108 offset:27648
	ds_read_b64_tr_b16 v[164:165], v108 offset:30208
	s_waitcnt lgkmcnt(8)
	v_exp_f32_e32 v91, v91
	v_add_f32_e64 v96, v88, 0
	v_cvt_pk_bf16_f32 v88, v88, v89
	v_add_f32_e32 v96, v90, v96
	v_add_f32_e32 v97, v91, v89
	v_exp_f32_e32 v98, v64
	v_exp_f32_e32 v99, v65
	v_cvt_pk_bf16_f32 v89, v90, v91
	v_cvt_pk_bf16_f32 v90, v66, v67
	v_cvt_pk_bf16_f32 v91, v98, v99
	v_add_f32_e32 v64, v66, v96
	v_add_f32_e32 v65, v67, v97
	v_mfma_f32_32x32x16_bf16 a[0:15], v[146:149], v[88:91], a[0:15]
	ds_read_b64_tr_b16 v[166:167], v108 offset:27712
	ds_read_b64_tr_b16 v[170:171], v108 offset:27776
	ds_read_b64_tr_b16 v[174:175], v108 offset:27840
	ds_read_b64_tr_b16 v[168:169], v108 offset:30272
	ds_read_b64_tr_b16 v[172:173], v108 offset:30336
	ds_read_b64_tr_b16 v[176:177], v108 offset:30400
	s_waitcnt lgkmcnt(10)
	v_mfma_f32_32x32x16_bf16 a[32:47], v[150:153], v[88:91], a[32:47]
	s_waitcnt lgkmcnt(9)
	v_fma_f32 v66, v210, s52, v48
	v_fma_f32 v67, v211, s52, v49
	v_exp_f32_e32 v66, v66
	v_exp_f32_e32 v67, v67
	v_mfma_f32_32x32x16_bf16 a[64:79], v[154:157], v[88:91], a[64:79]
	s_waitcnt lgkmcnt(8)
	v_add_f32_e32 v64, v98, v64
	v_add_f32_e32 v65, v99, v65
	v_fma_f32 v98, v216, s52, v48
	v_fma_f32 v99, v217, s52, v49
	v_fma_f32 v92, v212, s52, v48
	v_mfma_f32_32x32x16_bf16 a[96:111], v[158:161], v[88:91], a[96:111]
	s_waitcnt lgkmcnt(6)
	v_fma_f32 v93, v213, s52, v49
	v_exp_f32_e32 v98, v98
	v_exp_f32_e32 v94, v92
	v_exp_f32_e32 v95, v93
	v_cvt_pk_bf16_f32 v92, v66, v67
	v_exp_f32_e32 v99, v99
	v_add_f32_e64 v66, v94, v66
	v_add_f32_e64 v67, v95, v67
	v_fma_f32 v96, v214, s52, v48
	v_fma_f32 v97, v215, s52, v49
	v_exp_f32_e32 v96, v96
	v_exp_f32_e32 v97, v97
	v_cvt_pk_bf16_f32 v93, v94, v95
	v_cvt_pk_bf16_f32 v94, v96, v97
	v_cvt_pk_bf16_f32 v95, v98, v99
	v_exp_f32_e32 v75, v75
	v_fma_f32 v70, v222, s52, v48
	v_mfma_f32_32x32x16_bf16 a[0:15], v[162:165], v[92:95], a[0:15]
	ds_read_b64_tr_b16 v[178:179], v108 offset:32768
	ds_read_b64_tr_b16 v[180:181], v108 offset:35328
	ds_read_b64_tr_b16 v[182:183], v108 offset:32832
	ds_read_b64_tr_b16 v[186:187], v108 offset:32896
	ds_read_b64_tr_b16 v[190:191], v108 offset:32960
	ds_read_b64_tr_b16 v[184:185], v108 offset:35392
	ds_read_b64_tr_b16 v[188:189], v108 offset:35456
	ds_read_b64_tr_b16 v[192:193], v108 offset:35520
	s_waitcnt lgkmcnt(10)
	v_mfma_f32_32x32x16_bf16 a[32:47], v[166:169], v[92:95], a[32:47]
	s_waitcnt lgkmcnt(9)
	v_fma_f32 v71, v223, s52, v49
	v_exp_f32_e32 v88, v72
	v_exp_f32_e32 v89, v73
	v_mfma_f32_32x32x16_bf16 a[64:79], v[170:173], v[92:95], a[64:79]
	s_waitcnt lgkmcnt(8)
	v_exp_f32_e32 v70, v70
	v_exp_f32_e32 v71, v71
	v_fma_f32 v68, v224, s52, v48
	v_mfma_f32_32x32x16_bf16 a[96:111], v[174:177], v[92:95], a[96:111]
	s_waitcnt lgkmcnt(6)
	v_fma_f32 v69, v225, s52, v49
	v_cvt_pk_bf16_f32 v72, v74, v75
	v_add_f32_e64 v74, v88, v74
	v_add_f32_e64 v75, v89, v75
	v_exp_f32_e32 v90, v68
	v_exp_f32_e32 v91, v69
	v_add_f32_e32 v68, v70, v74
	v_add_f32_e32 v69, v71, v75
	v_cvt_pk_bf16_f32 v74, v70, v71
	v_cvt_pk_bf16_f32 v73, v88, v89
	v_cvt_pk_bf16_f32 v75, v90, v91
	v_add_f32_e32 v66, v96, v66
	v_add_f32_e32 v67, v97, v67
	v_mfma_f32_32x32x16_bf16 a[0:15], v[178:181], v[72:75], a[0:15]
	s_waitcnt lgkmcnt(2)
	v_add_f32_e64 v66, v98, v66
	v_add_f32_e64 v67, v99, v67
	v_fma_f32 v98, v226, s52, v52
	v_fma_f32 v99, v227, s52, v53
	v_fma_f32 v96, v228, s52, v52
	v_mfma_f32_32x32x16_bf16 a[32:47], v[182:185], v[72:75], a[32:47]
	s_waitcnt lgkmcnt(1)
	v_fma_f32 v97, v229, s52, v53
	v_fma_f32 v70, v232, s52, v52
	v_fma_f32 v71, v233, s52, v53
	v_exp_f32_e32 v104, v98
	v_mfma_f32_32x32x16_bf16 a[64:79], v[186:189], v[72:75], a[64:79]
	s_waitcnt lgkmcnt(0)
; DEV f32x16 mfma32(bf16x8 a, bf16x8 b, f32x16 c) { return __builtin_amdgcn_mfma_f32_32x32x16_bf16(a, b, c, 0, 0, 0); }
; template <bool SAMPLE>
; DEV void attn_unit(CParams& p, int layer, int unit, float lam, float lam_init, char* lds, const int swave) {
;     ...
;   auto lwrite = [&](int buf) {
;     char* ks_ = lds + buf * A_BUF; char* vs_ = ks_ + A_KT;
; #pragma unroll
;     for (int i = 0; i < 4; ++i) {
;       const int r = krow + 16 * i;
;       *(u32x4*)(ks_ + r * AK_B + kch * 16) = rk[i];
;       *(u32x4*)(vs_ + r * AV_B + kch * 16) = rv[i];
;     }
;   };
;     ...
; #pragma unroll
;       for (int sl = 0; sl < 4; ++sl)
; #pragma unroll
;         for (int e = 0; e < 4; ++e) {
;           const bf16x8 vf = tr8(Vs, AV_B, sl * 16, e * 32, lane);
;           O2[e] = mfma32(vf, pf[1][sl], O2[e]);
;         }
;     }
;     if (t >= my_tiles && (!SAMPLE || t + 1 < ntiles)) gloadV(tn);
;     if (!SAMPLE || t + 1 < ntiles) lwrite((t + 1) & 1);
;     __syncthreads();
	v_fma_f32 v94, v230, s52, v52
	v_fma_f32 v95, v231, s52, v53
	v_exp_f32_e32 v105, v99
	v_exp_f32_e32 v106, v96
	v_mfma_f32_32x32x16_bf16 a[96:111], v[190:193], v[72:75], a[96:111]
	v_exp_f32_e32 v107, v97
	v_exp_f32_e32 v108, v94
	v_exp_f32_e32 v109, v95
	v_exp_f32_e32 v74, v70
	v_exp_f32_e32 v75, v71
	v_cvt_pk_bf16_f32 v70, v104, v105
	v_cvt_pk_bf16_f32 v71, v106, v107
	v_cvt_pk_bf16_f32 v72, v108, v109
	v_cvt_pk_bf16_f32 v73, v74, v75
	v_add_f32_e32 v68, v90, v68
	v_add_f32_e32 v69, v91, v69
	v_mfma_f32_32x32x16_bf16 a[16:31], v[116:119], v[70:73], a[16:31]
	v_fma_f32 v94, v234, s52, v52
	v_fma_f32 v95, v235, s52, v53
	v_fma_f32 v92, v236, s52, v52
	v_fma_f32 v93, v237, s52, v53
	v_fma_f32 v90, v238, s52, v52
	v_fma_f32 v91, v239, s52, v53
	v_mfma_f32_32x32x16_bf16 a[48:63], v[100:103], v[70:73], a[48:63]
	v_exp_f32_e32 v120, v94
	v_exp_f32_e32 v121, v95
	v_mfma_f32_32x32x16_bf16 a[80:95], v[122:125], v[70:73], a[80:95]
	v_fma_f32 v132, v198, s52, v52
	v_fma_f32 v133, v199, s52, v53
	v_exp_f32_e32 v132, v132
	v_mfma_f32_32x32x16_bf16 a[112:127], v[142:145], v[70:73], a[112:127]
	v_cvt_pk_bf16_f32 v100, v120, v121
	v_exp_f32_e32 v122, v92
	v_exp_f32_e32 v123, v93
	v_exp_f32_e32 v124, v90
	v_exp_f32_e32 v125, v91
	v_cvt_pk_bf16_f32 v101, v122, v123
	v_fma_f32 v70, v240, s52, v52
	v_fma_f32 v71, v241, s52, v53
	v_cvt_pk_bf16_f32 v102, v124, v125
	v_exp_f32_e32 v126, v70
	v_exp_f32_e32 v127, v71
	s_nop 0
	v_cvt_pk_bf16_f32 v103, v126, v127
	v_add_f32_e64 v104, v106, v104
	v_add_f32_e64 v105, v107, v105
	v_mfma_f32_32x32x16_bf16 a[16:31], v[146:149], v[100:103], a[16:31]
	s_andn2_b32 s8, 1, s37
	s_mul_i32 s8, s8, 0x9400
	s_add_i32 s8, s8, 16
	s_waitcnt vmcnt(0)
	v_add3_u32 v54, s8, v77, v76
	ds_write_b128 v54, a[160:163]
	v_add_f32_e32 v104, v108, v104
	v_add_f32_e32 v105, v109, v105
	v_mfma_f32_32x32x16_bf16 a[48:63], v[150:153], v[100:103], a[48:63]
	v_add3_u32 v55, s8, v78, v76
	ds_write_b128 v55, a[144:147] offset:17408
	v_fma_f32 v106, v194, s52, v52
	v_fma_f32 v107, v195, s52, v53
	v_fma_f32 v108, v196, s52, v52
	v_fma_f32 v109, v197, s52, v53
	v_exp_f32_e32 v106, v106
	v_mfma_f32_32x32x16_bf16 a[80:95], v[154:157], v[100:103], a[80:95]
	v_add3_u32 v56, s8, v79, v76
	ds_write_b128 v56, a[164:167]
	v_mfma_f32_32x32x16_bf16 a[112:127], v[158:161], v[100:103], a[112:127]
	v_add3_u32 v57, s8, v80, v76
	ds_write_b128 v57, a[148:151] offset:17408
	v_exp_f32_e32 v107, v107
	v_exp_f32_e32 v108, v108
	v_exp_f32_e32 v109, v109
	v_exp_f32_e32 v133, v133
	v_fma_f32 v100, v200, s52, v52
	v_fma_f32 v101, v201, s52, v53
	v_cvt_pk_bf16_f32 v102, v132, v133
	v_exp_f32_e32 v118, v100
	v_exp_f32_e32 v119, v101
	v_cvt_pk_bf16_f32 v100, v106, v107
	v_cvt_pk_bf16_f32 v101, v108, v109
	v_cvt_pk_bf16_f32 v103, v118, v119
	v_add_f32_e32 v74, v74, v104
	v_add_f32_e32 v75, v75, v105
	v_mfma_f32_32x32x16_bf16 a[16:31], v[162:165], v[100:103], a[16:31]
	v_add3_u32 v58, s8, v81, v76
	ds_write_b128 v58, a[168:171]
	v_add_f32_e32 v104, v122, v120
	v_add_f32_e32 v105, v123, v121
	v_add_f32_e64 v104, v124, v104
	v_add_f32_e64 v105, v125, v105
	v_mfma_f32_32x32x16_bf16 a[48:63], v[166:169], v[100:103], a[48:63]
	v_add3_u32 v59, s8, v82, v76
	ds_write_b128 v59, a[152:155] offset:17408
	v_add_f32_e64 v120, v126, v104
	v_add_f32_e64 v121, v127, v105
	v_mfma_f32_32x32x16_bf16 a[80:95], v[170:173], v[100:103], a[80:95]
	v_add3_u32 v60, s8, v83, v76
	ds_write_b128 v60, a[172:175]
	v_add_f32_e64 v104, v108, v106
	v_mfma_f32_32x32x16_bf16 a[112:127], v[174:177], v[100:103], a[112:127]
	v_add3_u32 v61, s8, v84, v76
	ds_write_b128 v61, a[156:159] offset:17408
	v_add_f32_e64 v105, v109, v107
	v_fma_f32 v112, v206, s52, v52
	v_fma_f32 v113, v207, s52, v53
	v_add_f32_e32 v104, v132, v104
	v_add_f32_e32 v105, v133, v105
	v_exp_f32_e32 v112, v112
	v_exp_f32_e32 v113, v113
	v_fma_f32 v106, v202, s52, v52
	v_fma_f32 v107, v203, s52, v53
	v_exp_f32_e32 v106, v106
	v_exp_f32_e32 v107, v107
	v_fma_f32 v108, v204, s52, v52
	v_fma_f32 v109, v205, s52, v53
	v_add_f32_e64 v114, v118, v104
	v_add_f32_e64 v115, v119, v105
	v_exp_f32_e32 v108, v108
	v_exp_f32_e32 v109, v109
	v_add_f32_e64 v116, v106, 0
	v_add_f32_e64 v117, v107, 0
	v_cvt_pk_bf16_f32 v104, v106, v107
	v_add_f32_e32 v106, v108, v116
	v_add_f32_e32 v107, v109, v117
	v_cvt_pk_bf16_f32 v105, v108, v109
	v_fma_f32 v100, v208, s52, v52
	v_fma_f32 v101, v209, s52, v53
	v_add_f32_e64 v102, v112, v106
	v_add_f32_e64 v103, v113, v107
	v_exp_f32_e32 v100, v100
	v_exp_f32_e32 v101, v101
	v_cvt_pk_bf16_f32 v106, v112, v113
	v_cvt_pk_bf16_f32 v107, v100, v101
	v_add_f32_e64 v100, v100, v102
	v_add_f32_e64 v101, v101, v103
	v_mfma_f32_32x32x16_bf16 a[16:31], v[178:181], v[104:107], a[16:31]
	v_add_f32_e32 v62, v62, v63
	v_add_f32_e32 v74, v74, v75
	v_add_f32_e32 v64, v64, v65
	v_add_f32_e32 v120, v120, v121
	v_add_f32_e32 v66, v66, v67
	v_add_f32_e32 v114, v114, v115
	v_mfma_f32_32x32x16_bf16 a[48:63], v[182:185], v[104:107], a[48:63]
	v_add_f32_e32 v68, v68, v69
	v_add_f32_e32 v100, v100, v101
	v_add_f32_e32 v62, v130, v62
	v_add_f32_e32 v74, v131, v74
	v_add_f32_e32 v62, v64, v62
	v_add_f32_e32 v74, v120, v74
	v_mfma_f32_32x32x16_bf16 a[80:95], v[186:189], v[104:107], a[80:95]
	v_add_f32_e32 v62, v66, v62
	v_add_f32_e32 v74, v114, v74
	v_add_f32_e32 v130, v68, v62
	v_add_f32_e32 v131, v100, v74
	v_mfma_f32_32x32x16_bf16 a[112:127], v[190:193], v[104:107], a[112:127]
	s_branch .Lattn_tail
